# E1 identity init by one compare + DPP row shifts; stage D mask compares against inline constants (no per-row index registers)
# baseline (speedup 1.0000x reference)
.LBB0_967:
	s_setprio 0
	s_waitcnt lgkmcnt(0)
	s_barrier
	s_andn2_b64 vcc, exec, s[20:21]
	v_lshlrev_b32_e32 v98, 2, v115
	s_cbranch_vccnz .LBB0_1032
	v_mul_u32_u24_e32 v32, 0x48, v112
	v_lshlrev_b32_e32 v89, 1, v32
	v_add_u32_e32 v88, v89, v96
	ds_read_b128 v[32:35], v88 offset:16640
	v_add3_u32 v94, s42, v89, v96
	ds_read_b128 v[36:39], v94
	ds_read_b128 v[90:93], v88 offset:16672
	ds_read_b128 v[116:119], v94 offset:32
	v_cmp_lt_u32_e64 s[10:11], v112, v98
	s_mov_b64 s[36:37], -1
	s_and_b64 vcc, exec, s[30:31]
	s_waitcnt lgkmcnt(2)
	v_mfma_f32_32x32x16_bf16 v[32:47], v[32:35], v[36:39], 0
	s_waitcnt lgkmcnt(0)
	v_mfma_f32_32x32x16_bf16 v[32:47], v[90:93], v[116:119], v[32:47]
	ds_read_b128 v[90:93], v88 offset:16704
	ds_read_b128 v[116:119], v94 offset:64
	ds_read_b128 v[120:123], v88 offset:16736
	ds_read_b128 v[124:127], v94 offset:96
	v_lshl_add_u32 v88, v112, 1, s43
	s_waitcnt lgkmcnt(2)
	v_mfma_f32_32x32x16_bf16 v[32:47], v[90:93], v[116:119], v[32:47]
	s_waitcnt lgkmcnt(0)
	v_mfma_f32_32x32x16_bf16 v[32:47], v[120:123], v[124:127], v[32:47]
	v_sub_u32_e32 v213, v112, v98
	s_cmp_eq_u64 s[30:31], 0
	s_cbranch_scc1 .Ld_w0_a
	v_mul_u32_u24_e32 v89, 0x50, v98
	v_add_u32_e32 v89, v89, v88
	v_cmp_gt_i32_e32 vcc, 0, v213
	v_cmp_gt_i32_e64 s[10:11], 1, v213
	v_cmp_gt_i32_e64 s[36:37], 2, v213
	v_cndmask_b32_e64 v32, 0, v32, vcc
	v_cmp_gt_i32_e32 vcc, 3, v213
	v_cndmask_b32_e64 v33, 0, v33, s[10:11]
	v_cmp_gt_i32_e64 s[10:11], 8, v213
	v_cvt_pk_bf16_f32 v90, v32, v33
	ds_write_b16 v89, v90 offset:0
	ds_write_b16_d16_hi v89, v90 offset:80
	v_cndmask_b32_e64 v34, 0, v34, s[36:37]
	v_cmp_gt_i32_e64 s[36:37], 9, v213
	v_cndmask_b32_e64 v35, 0, v35, vcc
	v_cmp_gt_i32_e32 vcc, 10, v213
	v_cvt_pk_bf16_f32 v90, v34, v35
	ds_write_b16 v89, v90 offset:160
	ds_write_b16_d16_hi v89, v90 offset:240
	v_cndmask_b32_e64 v36, 0, v36, s[10:11]
	v_cmp_gt_i32_e64 s[10:11], 11, v213
	v_cndmask_b32_e64 v37, 0, v37, s[36:37]
	v_cmp_gt_i32_e64 s[36:37], 16, v213
	v_cvt_pk_bf16_f32 v90, v36, v37
	ds_write_b16 v89, v90 offset:640
	ds_write_b16_d16_hi v89, v90 offset:720
	v_cndmask_b32_e64 v38, 0, v38, vcc
	v_cmp_gt_i32_e32 vcc, 17, v213
	v_cndmask_b32_e64 v39, 0, v39, s[10:11]
	v_cmp_gt_i32_e64 s[10:11], 18, v213
	v_cvt_pk_bf16_f32 v90, v38, v39
	ds_write_b16 v89, v90 offset:800
	ds_write_b16_d16_hi v89, v90 offset:880
	v_cndmask_b32_e64 v40, 0, v40, s[36:37]
	v_cmp_gt_i32_e64 s[36:37], 19, v213
	v_cndmask_b32_e64 v41, 0, v41, vcc
	v_cmp_gt_i32_e32 vcc, 24, v213
	v_cvt_pk_bf16_f32 v90, v40, v41
	ds_write_b16 v89, v90 offset:1280
	ds_write_b16_d16_hi v89, v90 offset:1360
	v_cndmask_b32_e64 v42, 0, v42, s[10:11]
	v_cmp_gt_i32_e64 s[10:11], 25, v213
	v_cndmask_b32_e64 v43, 0, v43, s[36:37]
	v_cmp_gt_i32_e64 s[36:37], 26, v213
	v_cvt_pk_bf16_f32 v90, v42, v43
	ds_write_b16 v89, v90 offset:1440
	ds_write_b16_d16_hi v89, v90 offset:1520
	v_cndmask_b32_e64 v44, 0, v44, vcc
	v_cmp_gt_i32_e32 vcc, 27, v213
	v_cndmask_b32_e64 v45, 0, v45, s[10:11]
	v_cvt_pk_bf16_f32 v90, v44, v45
	ds_write_b16 v89, v90 offset:1920
	ds_write_b16_d16_hi v89, v90 offset:2000
	v_cndmask_b32_e64 v46, 0, v46, s[36:37]
	v_cndmask_b32_e64 v47, 0, v47, vcc
	v_cvt_pk_bf16_f32 v90, v46, v47
	ds_write_b16 v89, v90 offset:2080
	ds_write_b16_d16_hi v89, v90 offset:2160
	s_branch .Ld_done_a
.Ld_w0_a:
	s_setprio 3
	v_mul_u32_u24_e32 v89, 0x84, v112
	v_lshl_add_u32 v89, v98, 2, v89
	v_add_u32_e32 v89, 0x2080, v89
	v_cmp_gt_i32_e32 vcc, 0, v213
	v_cmp_gt_i32_e64 s[10:11], 1, v213
	v_cmp_gt_i32_e64 s[36:37], 2, v213
	v_cndmask_b32_e64 v32, 0, v32, vcc
	v_cmp_gt_i32_e32 vcc, 3, v213
	v_cndmask_b32_e64 v33, 0, v33, s[10:11]
	v_cmp_gt_i32_e64 s[10:11], 8, v213
	ds_write2_b32 v89, v32, v33 offset0:0 offset1:1
	v_cndmask_b32_e64 v34, 0, v34, s[36:37]
	v_cmp_gt_i32_e64 s[36:37], 9, v213
	v_cndmask_b32_e64 v35, 0, v35, vcc
	v_cmp_gt_i32_e32 vcc, 10, v213
	ds_write2_b32 v89, v34, v35 offset0:2 offset1:3
	v_cndmask_b32_e64 v36, 0, v36, s[10:11]
	v_cmp_gt_i32_e64 s[10:11], 11, v213
	v_cndmask_b32_e64 v37, 0, v37, s[36:37]
	v_cmp_gt_i32_e64 s[36:37], 16, v213
	ds_write2_b32 v89, v36, v37 offset0:8 offset1:9
	v_cndmask_b32_e64 v38, 0, v38, vcc
	v_cmp_gt_i32_e32 vcc, 17, v213
	v_cndmask_b32_e64 v39, 0, v39, s[10:11]
	v_cmp_gt_i32_e64 s[10:11], 18, v213
	ds_write2_b32 v89, v38, v39 offset0:10 offset1:11
	v_cndmask_b32_e64 v40, 0, v40, s[36:37]
	v_cmp_gt_i32_e64 s[36:37], 19, v213
	v_cndmask_b32_e64 v41, 0, v41, vcc
	v_cmp_gt_i32_e32 vcc, 24, v213
	ds_write2_b32 v89, v40, v41 offset0:16 offset1:17
	v_cndmask_b32_e64 v42, 0, v42, s[10:11]
	v_cmp_gt_i32_e64 s[10:11], 25, v213
	v_cndmask_b32_e64 v43, 0, v43, s[36:37]
	v_cmp_gt_i32_e64 s[36:37], 26, v213
	ds_write2_b32 v89, v42, v43 offset0:18 offset1:19
	v_cndmask_b32_e64 v44, 0, v44, vcc
	v_cmp_gt_i32_e32 vcc, 27, v213
	v_cndmask_b32_e64 v45, 0, v45, s[10:11]
	ds_write2_b32 v89, v44, v45 offset0:24 offset1:25
	v_cndmask_b32_e64 v46, 0, v46, s[36:37]
	v_cndmask_b32_e64 v47, 0, v47, vcc
	ds_write2_b32 v89, v46, v47 offset0:26 offset1:27
.Ld_done_a:
.LBB0_1032:
	v_cmp_gt_i32_e32 vcc, 32, v113
	v_and_b32_e32 v32, 15, v113
	s_and_saveexec_b64 s[36:37], vcc
	s_cbranch_execz .LBB0_1034
	v_lshrrev_b32_e32 v99, 4, v113
	v_mul_u32_u24_e32 v33, 0x880, v99
	v_add_u32_e32 v33, 0x2080, v33
	v_add_u32_e32 v96, 0x420, v33
	v_cmp_eq_u32_e32 vcc, 0, v32
	ds_read_b32 v116, v33 offset:4
	ds_read2_b32 v[118:119], v33 offset0:2 offset1:3
	v_cndmask_b32_e64 v34, 0, 1.0, vcc
	ds_read2_b32 v[120:121], v33 offset0:4 offset1:5
	ds_read2_b32 v[122:123], v33 offset0:6 offset1:7
	v_mov_b32_dpp v35, v34 row_shr:1 row_mask:0xf bank_mask:0xf bound_ctrl:1
	v_mov_b32_dpp v36, v34 row_shr:2 row_mask:0xf bank_mask:0xf bound_ctrl:1
	ds_read2_b32 v[124:125], v33 offset0:8 offset1:9
	v_mov_b32_dpp v37, v34 row_shr:3 row_mask:0xf bank_mask:0xf bound_ctrl:1
	v_mov_b32_dpp v38, v34 row_shr:4 row_mask:0xf bank_mask:0xf bound_ctrl:1
	ds_read2_b32 v[126:127], v33 offset0:10 offset1:11
	v_mov_b32_dpp v39, v34 row_shr:5 row_mask:0xf bank_mask:0xf bound_ctrl:1
	v_mov_b32_dpp v40, v34 row_shr:6 row_mask:0xf bank_mask:0xf bound_ctrl:1
	ds_read2_b32 v[88:89], v33 offset0:12 offset1:13
	v_mov_b32_dpp v41, v34 row_shr:7 row_mask:0xf bank_mask:0xf bound_ctrl:1
	v_mov_b32_dpp v42, v34 row_shr:8 row_mask:0xf bank_mask:0xf bound_ctrl:1
	ds_read2_b32 v[90:91], v33 offset0:14 offset1:15
	v_mov_b32_dpp v43, v34 row_shr:9 row_mask:0xf bank_mask:0xf bound_ctrl:1
	v_mov_b32_dpp v44, v34 row_shr:10 row_mask:0xf bank_mask:0xf bound_ctrl:1
	ds_read2_b32 v[92:93], v33 offset0:35 offset1:36
	v_mov_b32_dpp v45, v34 row_shr:11 row_mask:0xf bank_mask:0xf bound_ctrl:1
	v_mov_b32_dpp v46, v34 row_shr:12 row_mask:0xf bank_mask:0xf bound_ctrl:1
	ds_read2_b32 v[94:95], v33 offset0:37 offset1:38
	v_mov_b32_dpp v47, v34 row_shr:13 row_mask:0xf bank_mask:0xf bound_ctrl:1
	v_mov_b32_dpp v100, v34 row_shr:14 row_mask:0xf bank_mask:0xf bound_ctrl:1
	v_mov_b32_dpp v101, v34 row_shr:15 row_mask:0xf bank_mask:0xf bound_ctrl:1
	s_waitcnt lgkmcnt(6)
	v_fmac_f32_e32 v35, v34, v116
	v_pk_fma_f32 v[36:37], v[34:35], v[118:119], v[36:37] op_sel:[0,0,0] op_sel_hi:[0,1,1]
	v_pk_fma_f32 v[38:39], v[34:35], v[120:121], v[38:39] op_sel:[0,0,0] op_sel_hi:[0,1,1]
	v_pk_fma_f32 v[40:41], v[34:35], v[122:123], v[40:41] op_sel:[0,0,0] op_sel_hi:[0,1,1]
	ds_read2_b32 v[116:117], v33 offset0:39 offset1:40
	ds_read2_b32 v[118:119], v33 offset0:41 offset1:42
	ds_read2_b32 v[120:121], v33 offset0:43 offset1:44
	ds_read2_b32 v[122:123], v33 offset0:45 offset1:46
	s_waitcnt lgkmcnt(6)
	v_pk_fma_f32 v[42:43], v[34:35], v[124:125], v[42:43] op_sel:[0,0,0] op_sel_hi:[0,1,1]
	v_pk_fma_f32 v[44:45], v[34:35], v[126:127], v[44:45] op_sel:[0,0,0] op_sel_hi:[0,1,1]
	v_pk_fma_f32 v[46:47], v[34:35], v[88:89], v[46:47] op_sel:[0,0,0] op_sel_hi:[0,1,1]
	v_pk_fma_f32 v[100:101], v[34:35], v[90:91], v[100:101] op_sel:[0,0,0] op_sel_hi:[0,1,1]
	ds_read2_b32 v[124:125], v33 offset0:47 offset1:48
	ds_read_b32 v126, v33 offset:276
	ds_read2_b32 v[88:89], v33 offset0:70 offset1:71
	ds_read2_b32 v[90:91], v33 offset0:72 offset1:73
	s_waitcnt lgkmcnt(6)
	v_pk_fma_f32 v[36:37], v[34:35], v[92:93], v[36:37] op_sel:[1,0,0] op_sel_hi:[1,1,1]
	v_pk_fma_f32 v[38:39], v[34:35], v[94:95], v[38:39] op_sel:[1,0,0] op_sel_hi:[1,1,1]
	v_pk_fma_f32 v[40:41], v[34:35], v[116:117], v[40:41] op_sel:[1,0,0] op_sel_hi:[1,1,1]
	v_pk_fma_f32 v[42:43], v[34:35], v[118:119], v[42:43] op_sel:[1,0,0] op_sel_hi:[1,1,1]
	ds_read2_b32 v[92:93], v33 offset0:74 offset1:75
	ds_read2_b32 v[94:95], v33 offset0:76 offset1:77
	ds_read2_b32 v[116:117], v33 offset0:78 offset1:79
	ds_read2_b32 v[118:119], v33 offset0:80 offset1:81
	s_waitcnt lgkmcnt(6)
	v_pk_fma_f32 v[44:45], v[34:35], v[120:121], v[44:45] op_sel:[1,0,0] op_sel_hi:[1,1,1]
	v_pk_fma_f32 v[46:47], v[34:35], v[122:123], v[46:47] op_sel:[1,0,0] op_sel_hi:[1,1,1]
	v_pk_fma_f32 v[100:101], v[34:35], v[124:125], v[100:101] op_sel:[1,0,0] op_sel_hi:[1,1,1]
	v_fmac_f32_e32 v37, v36, v126
	ds_read2_b32 v[120:121], v33 offset0:103 offset1:104
	ds_read2_b32 v[122:123], v33 offset0:105 offset1:106
	ds_read2_b32 v[124:125], v33 offset0:107 offset1:108
	ds_read2_b32 v[126:127], v33 offset0:109 offset1:110
	s_waitcnt lgkmcnt(6)
	v_pk_fma_f32 v[38:39], v[36:37], v[88:89], v[38:39] op_sel:[0,0,0] op_sel_hi:[0,1,1]
	v_pk_fma_f32 v[40:41], v[36:37], v[90:91], v[40:41] op_sel:[0,0,0] op_sel_hi:[0,1,1]
	v_pk_fma_f32 v[42:43], v[36:37], v[92:93], v[42:43] op_sel:[0,0,0] op_sel_hi:[0,1,1]
	v_pk_fma_f32 v[44:45], v[36:37], v[94:95], v[44:45] op_sel:[0,0,0] op_sel_hi:[0,1,1]
	ds_read2_b32 v[88:89], v33 offset0:111 offset1:112
	ds_read2_b32 v[90:91], v33 offset0:113 offset1:114
	ds_read_b32 v92, v33 offset:548
	ds_read2_b32 v[94:95], v33 offset0:138 offset1:139
	s_waitcnt lgkmcnt(6)
	v_pk_fma_f32 v[46:47], v[36:37], v[116:117], v[46:47] op_sel:[0,0,0] op_sel_hi:[0,1,1]
	v_pk_fma_f32 v[100:101], v[36:37], v[118:119], v[100:101] op_sel:[0,0,0] op_sel_hi:[0,1,1]
	v_pk_fma_f32 v[38:39], v[36:37], v[120:121], v[38:39] op_sel:[1,0,0] op_sel_hi:[1,1,1]
	v_pk_fma_f32 v[40:41], v[36:37], v[122:123], v[40:41] op_sel:[1,0,0] op_sel_hi:[1,1,1]
	ds_read2_b32 v[116:117], v33 offset0:140 offset1:141
	ds_read2_b32 v[118:119], v33 offset0:142 offset1:143
	ds_read2_b32 v[120:121], v33 offset0:144 offset1:145
	ds_read2_b32 v[122:123], v33 offset0:146 offset1:147
	s_waitcnt lgkmcnt(6)
	v_pk_fma_f32 v[42:43], v[36:37], v[124:125], v[42:43] op_sel:[1,0,0] op_sel_hi:[1,1,1]
	v_pk_fma_f32 v[44:45], v[36:37], v[126:127], v[44:45] op_sel:[1,0,0] op_sel_hi:[1,1,1]
	v_pk_fma_f32 v[46:47], v[36:37], v[88:89], v[46:47] op_sel:[1,0,0] op_sel_hi:[1,1,1]
	v_pk_fma_f32 v[100:101], v[36:37], v[90:91], v[100:101] op_sel:[1,0,0] op_sel_hi:[1,1,1]
	ds_read2_b32 v[124:125], v33 offset0:171 offset1:172
	ds_read2_b32 v[126:127], v33 offset0:173 offset1:174
	ds_read2_b32 v[88:89], v33 offset0:175 offset1:176
	ds_read2_b32 v[90:91], v33 offset0:177 offset1:178
	s_waitcnt lgkmcnt(6)
	v_fmac_f32_e32 v39, v38, v92
	v_pk_fma_f32 v[40:41], v[38:39], v[94:95], v[40:41] op_sel:[0,0,0] op_sel_hi:[0,1,1]
	v_pk_fma_f32 v[42:43], v[38:39], v[116:117], v[42:43] op_sel:[0,0,0] op_sel_hi:[0,1,1]
	v_pk_fma_f32 v[44:45], v[38:39], v[118:119], v[44:45] op_sel:[0,0,0] op_sel_hi:[0,1,1]
	ds_read2_b32 v[92:93], v33 offset0:179 offset1:180
	ds_read_b32 v94, v33 offset:820
	ds_read2_b32 v[116:117], v33 offset0:206 offset1:207
	ds_read2_b32 v[118:119], v33 offset0:208 offset1:209
	s_waitcnt lgkmcnt(6)
	v_pk_fma_f32 v[46:47], v[38:39], v[120:121], v[46:47] op_sel:[0,0,0] op_sel_hi:[0,1,1]
	v_pk_fma_f32 v[100:101], v[38:39], v[122:123], v[100:101] op_sel:[0,0,0] op_sel_hi:[0,1,1]
	v_pk_fma_f32 v[40:41], v[38:39], v[124:125], v[40:41] op_sel:[1,0,0] op_sel_hi:[1,1,1]
	v_pk_fma_f32 v[42:43], v[38:39], v[126:127], v[42:43] op_sel:[1,0,0] op_sel_hi:[1,1,1]
	ds_read2_b32 v[120:121], v33 offset0:210 offset1:211
	ds_read2_b32 v[122:123], v33 offset0:212 offset1:213
	ds_read2_b32 v[124:125], v33 offset0:239 offset1:240
	ds_read2_b32 v[126:127], v33 offset0:241 offset1:242
	s_waitcnt lgkmcnt(6)
	v_pk_fma_f32 v[44:45], v[38:39], v[88:89], v[44:45] op_sel:[1,0,0] op_sel_hi:[1,1,1]
	v_pk_fma_f32 v[46:47], v[38:39], v[90:91], v[46:47] op_sel:[1,0,0] op_sel_hi:[1,1,1]
	v_pk_fma_f32 v[100:101], v[38:39], v[92:93], v[100:101] op_sel:[1,0,0] op_sel_hi:[1,1,1]
	v_fmac_f32_e32 v41, v40, v94
	ds_read2_b32 v[88:89], v33 offset0:243 offset1:244
	ds_read2_b32 v[90:91], v33 offset0:245 offset1:246
	ds_read_b32 v92, v96 offset:36
	ds_read2_b32 v[94:95], v96 offset0:10 offset1:11
	s_waitcnt lgkmcnt(6)
	v_pk_fma_f32 v[42:43], v[40:41], v[116:117], v[42:43] op_sel:[0,0,0] op_sel_hi:[0,1,1]
	v_pk_fma_f32 v[44:45], v[40:41], v[118:119], v[44:45] op_sel:[0,0,0] op_sel_hi:[0,1,1]
	v_pk_fma_f32 v[46:47], v[40:41], v[120:121], v[46:47] op_sel:[0,0,0] op_sel_hi:[0,1,1]
	v_pk_fma_f32 v[100:101], v[40:41], v[122:123], v[100:101] op_sel:[0,0,0] op_sel_hi:[0,1,1]
	ds_read2_b32 v[116:117], v96 offset0:12 offset1:13
	ds_read2_b32 v[118:119], v96 offset0:14 offset1:15
	ds_read2_b32 v[120:121], v96 offset0:43 offset1:44
	ds_read2_b32 v[122:123], v96 offset0:45 offset1:46
	s_waitcnt lgkmcnt(6)
	v_pk_fma_f32 v[42:43], v[40:41], v[124:125], v[42:43] op_sel:[1,0,0] op_sel_hi:[1,1,1]
	v_pk_fma_f32 v[44:45], v[40:41], v[126:127], v[44:45] op_sel:[1,0,0] op_sel_hi:[1,1,1]
	v_pk_fma_f32 v[46:47], v[40:41], v[88:89], v[46:47] op_sel:[1,0,0] op_sel_hi:[1,1,1]
	v_pk_fma_f32 v[100:101], v[40:41], v[90:91], v[100:101] op_sel:[1,0,0] op_sel_hi:[1,1,1]
	ds_read2_b32 v[124:125], v96 offset0:47 offset1:48
	ds_read_b32 v126, v96 offset:308
	ds_read2_b32 v[88:89], v96 offset0:78 offset1:79
	ds_read2_b32 v[90:91], v96 offset0:80 offset1:81
	s_waitcnt lgkmcnt(6)
	v_fmac_f32_e32 v43, v42, v92
	v_pk_fma_f32 v[44:45], v[42:43], v[94:95], v[44:45] op_sel:[0,0,0] op_sel_hi:[0,1,1]
	v_pk_fma_f32 v[46:47], v[42:43], v[116:117], v[46:47] op_sel:[0,0,0] op_sel_hi:[0,1,1]
	v_pk_fma_f32 v[100:101], v[42:43], v[118:119], v[100:101] op_sel:[0,0,0] op_sel_hi:[0,1,1]
	ds_read2_b32 v[92:93], v96 offset0:111 offset1:112
	ds_read2_b32 v[94:95], v96 offset0:113 offset1:114
	ds_read_b32 v116, v96 offset:580
	ds_read2_b32 v[118:119], v96 offset0:146 offset1:147
	s_waitcnt lgkmcnt(6)
	v_pk_fma_f32 v[44:45], v[42:43], v[120:121], v[44:45] op_sel:[1,0,0] op_sel_hi:[1,1,1]
	v_pk_fma_f32 v[46:47], v[42:43], v[122:123], v[46:47] op_sel:[1,0,0] op_sel_hi:[1,1,1]
	v_pk_fma_f32 v[100:101], v[42:43], v[124:125], v[100:101] op_sel:[1,0,0] op_sel_hi:[1,1,1]
	v_fmac_f32_e32 v45, v44, v126
	ds_read2_b32 v[120:121], v96 offset0:179 offset1:180
	ds_read_b32 v122, v96 offset:852
	s_waitcnt lgkmcnt(4)
	v_pk_fma_f32 v[46:47], v[44:45], v[88:89], v[46:47] op_sel:[0,0,0] op_sel_hi:[0,1,1]
	v_pk_fma_f32 v[100:101], v[44:45], v[90:91], v[100:101] op_sel:[0,0,0] op_sel_hi:[0,1,1]
	v_pk_fma_f32 v[46:47], v[44:45], v[92:93], v[46:47] op_sel:[1,0,0] op_sel_hi:[1,1,1]
	v_pk_fma_f32 v[100:101], v[44:45], v[94:95], v[100:101] op_sel:[1,0,0] op_sel_hi:[1,1,1]
	s_waitcnt lgkmcnt(0)
	v_fmac_f32_e32 v47, v46, v116
	v_pk_fma_f32 v[100:101], v[46:47], v[118:119], v[100:101] op_sel:[0,0,0] op_sel_hi:[0,1,1]
	v_pk_fma_f32 v[100:101], v[46:47], v[120:121], v[100:101] op_sel:[1,0,0] op_sel_hi:[1,1,1]
	v_fmac_f32_e32 v101, v100, v122
	v_mul_u32_u24_e32 v33, 0x440, v99
	v_mul_u32_u24_e32 v96, 0x520, v99
	v_mul_u32_u24_e32 v99, 0x44, v32
	v_add_u32_e32 v33, v33, v99
	v_lshl_add_u32 v96, v32, 1, v96
	v_add_u32_e32 v33, 0x3100, v33
	v_add_u32_e32 v96, 0xe3c0, v96
	ds_write2_b32 v33, v34, v35 offset0:0 offset1:1
	ds_write2_b32 v33, v36, v37 offset0:2 offset1:3
	ds_write2_b32 v33, v38, v39 offset0:4 offset1:5
	ds_write2_b32 v33, v40, v41 offset0:6 offset1:7
	ds_write2_b32 v33, v42, v43 offset0:8 offset1:9
	ds_write2_b32 v33, v44, v45 offset0:10 offset1:11
	ds_write2_b32 v33, v46, v47 offset0:12 offset1:13
	ds_write2_b32 v33, v100, v101 offset0:14 offset1:15
	v_cvt_pk_bf16_f32 v116, v34, v35
	ds_write_b16 v96, v116 offset:0
	ds_write_b16_d16_hi v96, v116 offset:80
	v_cvt_pk_bf16_f32 v118, v36, v37
	ds_write_b16 v96, v118 offset:160
	ds_write_b16_d16_hi v96, v118 offset:240
	v_cvt_pk_bf16_f32 v120, v38, v39
	ds_write_b16 v96, v120 offset:320
	ds_write_b16_d16_hi v96, v120 offset:400
	v_cvt_pk_bf16_f32 v122, v40, v41
	ds_write_b16 v96, v122 offset:480
	ds_write_b16_d16_hi v96, v122 offset:560
	v_cvt_pk_bf16_f32 v124, v42, v43
	ds_write_b16 v96, v124 offset:640
	ds_write_b16_d16_hi v96, v124 offset:720
	v_cvt_pk_bf16_f32 v126, v44, v45
	ds_write_b16 v96, v126 offset:800
	ds_write_b16_d16_hi v96, v126 offset:880
	v_cvt_pk_bf16_f32 v88, v46, v47
	ds_write_b16 v96, v88 offset:960
	ds_write_b16_d16_hi v96, v88 offset:1040
	v_cvt_pk_bf16_f32 v90, v100, v101
	ds_write_b16 v96, v90 offset:1120
	ds_write_b16_d16_hi v96, v90 offset:1200

.Lpf_skip_b:
	v_add3_u32 v50, s89, v66, v0
	ds_read_b128 v[34:37], v50
	v_add3_u32 v0, s90, v66, v0
	ds_read_b128 v[38:41], v0
	ds_read_b128 v[52:55], v50 offset:32
	ds_read_b128 v[56:59], v0 offset:32
	s_mov_b64 s[58:59], -1
	s_and_b64 vcc, exec, s[54:55]
	s_waitcnt lgkmcnt(2)
	v_mfma_f32_32x32x16_bf16 v[34:49], v[34:37], v[38:41], 0
	s_waitcnt lgkmcnt(0)
	v_mfma_f32_32x32x16_bf16 v[34:49], v[52:55], v[56:59], v[34:49]
	ds_read_b128 v[52:55], v50 offset:64
	ds_read_b128 v[56:59], v0 offset:64
	ds_read_b128 v[60:63], v50 offset:96
	ds_read_b128 v[72:75], v0 offset:96
	v_lshlrev_b32_e32 v0, 2, v51
	v_cmp_lt_u32_e64 s[12:13], v70, v0
	v_lshl_add_u32 v50, v70, 1, s91
	s_waitcnt lgkmcnt(2)
	v_mfma_f32_32x32x16_bf16 v[34:49], v[52:55], v[56:59], v[34:49]
	v_cndmask_b32_e64 v52, 0, 1, s[12:13]
	v_cmp_le_u32_e64 s[12:13], v70, v0
	s_nop 1
	v_cndmask_b32_e64 v53, 0, 1, s[12:13]
	v_cndmask_b32_e64 v52, v53, v52, s[8:9]
	v_and_b32_e32 v52, 1, v52
	s_waitcnt lgkmcnt(0)
	v_mfma_f32_32x32x16_bf16 v[34:49], v[60:63], v[72:75], v[34:49]
	v_sub_u32_e32 v143, v70, v0
	s_cmp_eq_u64 s[54:55], 0
	s_cbranch_scc1 .Ld_w0_b
	s_cmp_lg_u32 s89, s69
	s_cbranch_scc1 .Ld_w23_b
	v_mul_u32_u24_e32 v52, 0x50, v0
	v_add_u32_e32 v52, v52, v50
	v_cmp_gt_i32_e32 vcc, 0, v143
	v_cmp_gt_i32_e64 s[12:13], 1, v143
	v_cmp_gt_i32_e64 s[58:59], 2, v143
	v_cndmask_b32_e64 v34, 0, v34, vcc
	v_cmp_gt_i32_e32 vcc, 3, v143
	v_cndmask_b32_e64 v35, 0, v35, s[12:13]
	v_cmp_gt_i32_e64 s[12:13], 8, v143
	v_cvt_pk_bf16_f32 v53, v34, v35
	ds_write_b16 v52, v53 offset:0
	ds_write_b16_d16_hi v52, v53 offset:80
	v_cndmask_b32_e64 v36, 0, v36, s[58:59]
	v_cmp_gt_i32_e64 s[58:59], 9, v143
	v_cndmask_b32_e64 v37, 0, v37, vcc
	v_cmp_gt_i32_e32 vcc, 10, v143
	v_cvt_pk_bf16_f32 v53, v36, v37
	ds_write_b16 v52, v53 offset:160
	ds_write_b16_d16_hi v52, v53 offset:240
	v_cndmask_b32_e64 v38, 0, v38, s[12:13]
	v_cmp_gt_i32_e64 s[12:13], 11, v143
	v_cndmask_b32_e64 v39, 0, v39, s[58:59]
	v_cmp_gt_i32_e64 s[58:59], 16, v143
	v_cvt_pk_bf16_f32 v53, v38, v39
	ds_write_b16 v52, v53 offset:640
	ds_write_b16_d16_hi v52, v53 offset:720
	v_cndmask_b32_e64 v40, 0, v40, vcc
	v_cmp_gt_i32_e32 vcc, 17, v143
	v_cndmask_b32_e64 v41, 0, v41, s[12:13]
	v_cmp_gt_i32_e64 s[12:13], 18, v143
	v_cvt_pk_bf16_f32 v53, v40, v41
	ds_write_b16 v52, v53 offset:800
	ds_write_b16_d16_hi v52, v53 offset:880
	v_cndmask_b32_e64 v42, 0, v42, s[58:59]
	v_cmp_gt_i32_e64 s[58:59], 19, v143
	v_cndmask_b32_e64 v43, 0, v43, vcc
	v_cmp_gt_i32_e32 vcc, 24, v143
	v_cvt_pk_bf16_f32 v53, v42, v43
	ds_write_b16 v52, v53 offset:1280
	ds_write_b16_d16_hi v52, v53 offset:1360
	v_cndmask_b32_e64 v44, 0, v44, s[12:13]
	v_cmp_gt_i32_e64 s[12:13], 25, v143
	v_cndmask_b32_e64 v45, 0, v45, s[58:59]
	v_cmp_gt_i32_e64 s[58:59], 26, v143
	v_cvt_pk_bf16_f32 v53, v44, v45
	ds_write_b16 v52, v53 offset:1440
	ds_write_b16_d16_hi v52, v53 offset:1520
	v_cndmask_b32_e64 v46, 0, v46, vcc
	v_cmp_gt_i32_e32 vcc, 27, v143
	v_cndmask_b32_e64 v47, 0, v47, s[12:13]
	v_cvt_pk_bf16_f32 v53, v46, v47
	ds_write_b16 v52, v53 offset:1920
	ds_write_b16_d16_hi v52, v53 offset:2000
	v_cndmask_b32_e64 v48, 0, v48, s[58:59]
	v_cndmask_b32_e64 v49, 0, v49, vcc
	v_cvt_pk_bf16_f32 v53, v48, v49
	ds_write_b16 v52, v53 offset:2080
	ds_write_b16_d16_hi v52, v53 offset:2160
	s_branch .Ld_done_b
.Ld_w23_b:
	v_mul_u32_u24_e32 v52, 0x50, v0
	v_add_u32_e32 v52, v52, v50
	v_cmp_ge_i32_e32 vcc, 0, v143
	v_cmp_ge_i32_e64 s[12:13], 1, v143
	v_cmp_ge_i32_e64 s[58:59], 2, v143
	v_cndmask_b32_e64 v34, 0, v34, vcc
	v_cmp_ge_i32_e32 vcc, 3, v143
	v_cndmask_b32_e64 v35, 0, v35, s[12:13]
	v_cmp_ge_i32_e64 s[12:13], 8, v143
	v_cvt_pk_bf16_f32 v53, v34, v35
	ds_write_b16 v52, v53 offset:0
	ds_write_b16_d16_hi v52, v53 offset:80
	v_cndmask_b32_e64 v36, 0, v36, s[58:59]
	v_cmp_ge_i32_e64 s[58:59], 9, v143
	v_cndmask_b32_e64 v37, 0, v37, vcc
	v_cmp_ge_i32_e32 vcc, 10, v143
	v_cvt_pk_bf16_f32 v53, v36, v37
	ds_write_b16 v52, v53 offset:160
	ds_write_b16_d16_hi v52, v53 offset:240
	v_cndmask_b32_e64 v38, 0, v38, s[12:13]
	v_cmp_ge_i32_e64 s[12:13], 11, v143
	v_cndmask_b32_e64 v39, 0, v39, s[58:59]
	v_cmp_ge_i32_e64 s[58:59], 16, v143
	v_cvt_pk_bf16_f32 v53, v38, v39
	ds_write_b16 v52, v53 offset:640
	ds_write_b16_d16_hi v52, v53 offset:720
	v_cndmask_b32_e64 v40, 0, v40, vcc
	v_cmp_ge_i32_e32 vcc, 17, v143
	v_cndmask_b32_e64 v41, 0, v41, s[12:13]
	v_cmp_ge_i32_e64 s[12:13], 18, v143
	v_cvt_pk_bf16_f32 v53, v40, v41
	ds_write_b16 v52, v53 offset:800
	ds_write_b16_d16_hi v52, v53 offset:880
	v_cndmask_b32_e64 v42, 0, v42, s[58:59]
	v_cmp_ge_i32_e64 s[58:59], 19, v143
	v_cndmask_b32_e64 v43, 0, v43, vcc
	v_cmp_ge_i32_e32 vcc, 24, v143
	v_cvt_pk_bf16_f32 v53, v42, v43
	ds_write_b16 v52, v53 offset:1280
	ds_write_b16_d16_hi v52, v53 offset:1360
	v_cndmask_b32_e64 v44, 0, v44, s[12:13]
	v_cmp_ge_i32_e64 s[12:13], 25, v143
	v_cndmask_b32_e64 v45, 0, v45, s[58:59]
	v_cmp_ge_i32_e64 s[58:59], 26, v143
	v_cvt_pk_bf16_f32 v53, v44, v45
	ds_write_b16 v52, v53 offset:1440
	ds_write_b16_d16_hi v52, v53 offset:1520
	v_cndmask_b32_e64 v46, 0, v46, vcc
	v_cmp_ge_i32_e32 vcc, 27, v143
	v_cndmask_b32_e64 v47, 0, v47, s[12:13]
	v_cvt_pk_bf16_f32 v53, v46, v47
	ds_write_b16 v52, v53 offset:1920
	ds_write_b16_d16_hi v52, v53 offset:2000
	v_cndmask_b32_e64 v48, 0, v48, s[58:59]
	v_cndmask_b32_e64 v49, 0, v49, vcc
	v_cvt_pk_bf16_f32 v53, v48, v49
	ds_write_b16 v52, v53 offset:2080
	ds_write_b16_d16_hi v52, v53 offset:2160
	s_branch .Ld_done_b
.Ld_w0_b:
	s_setprio 3
	v_mul_u32_u24_e32 v52, 0x84, v70
	v_lshl_add_u32 v52, v0, 2, v52
	v_add_u32_e32 v52, 0x2080, v52
	v_cmp_gt_i32_e32 vcc, 0, v143
	v_cmp_gt_i32_e64 s[12:13], 1, v143
	v_cmp_gt_i32_e64 s[58:59], 2, v143
	v_cndmask_b32_e64 v34, 0, v34, vcc
	v_cmp_gt_i32_e32 vcc, 3, v143
	v_cndmask_b32_e64 v35, 0, v35, s[12:13]
	v_cmp_gt_i32_e64 s[12:13], 8, v143
	ds_write2_b32 v52, v34, v35 offset0:0 offset1:1
	v_cndmask_b32_e64 v36, 0, v36, s[58:59]
	v_cmp_gt_i32_e64 s[58:59], 9, v143
	v_cndmask_b32_e64 v37, 0, v37, vcc
	v_cmp_gt_i32_e32 vcc, 10, v143
	ds_write2_b32 v52, v36, v37 offset0:2 offset1:3
	v_cndmask_b32_e64 v38, 0, v38, s[12:13]
	v_cmp_gt_i32_e64 s[12:13], 11, v143
	v_cndmask_b32_e64 v39, 0, v39, s[58:59]
	v_cmp_gt_i32_e64 s[58:59], 16, v143
	ds_write2_b32 v52, v38, v39 offset0:8 offset1:9
	v_cndmask_b32_e64 v40, 0, v40, vcc
	v_cmp_gt_i32_e32 vcc, 17, v143
	v_cndmask_b32_e64 v41, 0, v41, s[12:13]
	v_cmp_gt_i32_e64 s[12:13], 18, v143
	ds_write2_b32 v52, v40, v41 offset0:10 offset1:11
	v_cndmask_b32_e64 v42, 0, v42, s[58:59]
	v_cmp_gt_i32_e64 s[58:59], 19, v143
	v_cndmask_b32_e64 v43, 0, v43, vcc
	v_cmp_gt_i32_e32 vcc, 24, v143
	ds_write2_b32 v52, v42, v43 offset0:16 offset1:17
	v_cndmask_b32_e64 v44, 0, v44, s[12:13]
	v_cmp_gt_i32_e64 s[12:13], 25, v143
	v_cndmask_b32_e64 v45, 0, v45, s[58:59]
	v_cmp_gt_i32_e64 s[58:59], 26, v143
	ds_write2_b32 v52, v44, v45 offset0:18 offset1:19
	v_cndmask_b32_e64 v46, 0, v46, vcc
	v_cmp_gt_i32_e32 vcc, 27, v143
	v_cndmask_b32_e64 v47, 0, v47, s[12:13]
	ds_write2_b32 v52, v46, v47 offset0:24 offset1:25
	v_cndmask_b32_e64 v48, 0, v48, s[58:59]
	v_cndmask_b32_e64 v49, 0, v49, vcc
	ds_write2_b32 v52, v48, v49 offset0:26 offset1:27

.LBB0_1212:
	v_bfe_u32 v67, v141, 4, 1
	v_mul_u32_u24_e32 v35, 0x880, v67
	v_add_u32_e32 v35, 0x2080, v35
	v_add_u32_e32 v50, 0x420, v35
	v_cmp_eq_u32_e32 vcc, 0, v34
	ds_read_b32 v52, v35 offset:4
	ds_read2_b32 v[54:55], v35 offset0:2 offset1:3
	v_cndmask_b32_e64 v36, 0, 1.0, vcc
	ds_read2_b32 v[56:57], v35 offset0:4 offset1:5
	ds_read2_b32 v[58:59], v35 offset0:6 offset1:7
	v_mov_b32_dpp v37, v36 row_shr:1 row_mask:0xf bank_mask:0xf bound_ctrl:1
	v_mov_b32_dpp v38, v36 row_shr:2 row_mask:0xf bank_mask:0xf bound_ctrl:1
	ds_read2_b32 v[60:61], v35 offset0:8 offset1:9
	v_mov_b32_dpp v39, v36 row_shr:3 row_mask:0xf bank_mask:0xf bound_ctrl:1
	v_mov_b32_dpp v40, v36 row_shr:4 row_mask:0xf bank_mask:0xf bound_ctrl:1
	ds_read2_b32 v[62:63], v35 offset0:10 offset1:11
	v_mov_b32_dpp v41, v36 row_shr:5 row_mask:0xf bank_mask:0xf bound_ctrl:1
	v_mov_b32_dpp v42, v36 row_shr:6 row_mask:0xf bank_mask:0xf bound_ctrl:1
	ds_read2_b32 v[64:65], v35 offset0:12 offset1:13
	v_mov_b32_dpp v43, v36 row_shr:7 row_mask:0xf bank_mask:0xf bound_ctrl:1
	v_mov_b32_dpp v44, v36 row_shr:8 row_mask:0xf bank_mask:0xf bound_ctrl:1
	ds_read2_b32 v[72:73], v35 offset0:14 offset1:15
	v_mov_b32_dpp v45, v36 row_shr:9 row_mask:0xf bank_mask:0xf bound_ctrl:1
	v_mov_b32_dpp v46, v36 row_shr:10 row_mask:0xf bank_mask:0xf bound_ctrl:1
	ds_read2_b32 v[74:75], v35 offset0:35 offset1:36
	v_mov_b32_dpp v47, v36 row_shr:11 row_mask:0xf bank_mask:0xf bound_ctrl:1
	v_mov_b32_dpp v48, v36 row_shr:12 row_mask:0xf bank_mask:0xf bound_ctrl:1
	ds_read2_b32 v[76:77], v35 offset0:37 offset1:38
	v_mov_b32_dpp v49, v36 row_shr:13 row_mask:0xf bank_mask:0xf bound_ctrl:1
	v_mov_b32_dpp v68, v36 row_shr:14 row_mask:0xf bank_mask:0xf bound_ctrl:1
	v_mov_b32_dpp v69, v36 row_shr:15 row_mask:0xf bank_mask:0xf bound_ctrl:1
	s_waitcnt lgkmcnt(6)
	v_fmac_f32_e32 v37, v36, v52
	v_pk_fma_f32 v[38:39], v[36:37], v[54:55], v[38:39] op_sel:[0,0,0] op_sel_hi:[0,1,1]
	v_pk_fma_f32 v[40:41], v[36:37], v[56:57], v[40:41] op_sel:[0,0,0] op_sel_hi:[0,1,1]
	v_pk_fma_f32 v[42:43], v[36:37], v[58:59], v[42:43] op_sel:[0,0,0] op_sel_hi:[0,1,1]
	ds_read2_b32 v[52:53], v35 offset0:39 offset1:40
	ds_read2_b32 v[54:55], v35 offset0:41 offset1:42
	ds_read2_b32 v[56:57], v35 offset0:43 offset1:44
	ds_read2_b32 v[58:59], v35 offset0:45 offset1:46
	s_waitcnt lgkmcnt(6)
	v_pk_fma_f32 v[44:45], v[36:37], v[60:61], v[44:45] op_sel:[0,0,0] op_sel_hi:[0,1,1]
	v_pk_fma_f32 v[46:47], v[36:37], v[62:63], v[46:47] op_sel:[0,0,0] op_sel_hi:[0,1,1]
	v_pk_fma_f32 v[48:49], v[36:37], v[64:65], v[48:49] op_sel:[0,0,0] op_sel_hi:[0,1,1]
	v_pk_fma_f32 v[68:69], v[36:37], v[72:73], v[68:69] op_sel:[0,0,0] op_sel_hi:[0,1,1]
	ds_read2_b32 v[60:61], v35 offset0:47 offset1:48
	ds_read_b32 v62, v35 offset:276
	ds_read2_b32 v[64:65], v35 offset0:70 offset1:71
	ds_read2_b32 v[72:73], v35 offset0:72 offset1:73
	s_waitcnt lgkmcnt(6)
	v_pk_fma_f32 v[38:39], v[36:37], v[74:75], v[38:39] op_sel:[1,0,0] op_sel_hi:[1,1,1]
	v_pk_fma_f32 v[40:41], v[36:37], v[76:77], v[40:41] op_sel:[1,0,0] op_sel_hi:[1,1,1]
	v_pk_fma_f32 v[42:43], v[36:37], v[52:53], v[42:43] op_sel:[1,0,0] op_sel_hi:[1,1,1]
	v_pk_fma_f32 v[44:45], v[36:37], v[54:55], v[44:45] op_sel:[1,0,0] op_sel_hi:[1,1,1]
	ds_read2_b32 v[74:75], v35 offset0:74 offset1:75
	ds_read2_b32 v[76:77], v35 offset0:76 offset1:77
	ds_read2_b32 v[52:53], v35 offset0:78 offset1:79
	ds_read2_b32 v[54:55], v35 offset0:80 offset1:81
	s_waitcnt lgkmcnt(6)
	v_pk_fma_f32 v[46:47], v[36:37], v[56:57], v[46:47] op_sel:[1,0,0] op_sel_hi:[1,1,1]
	v_pk_fma_f32 v[48:49], v[36:37], v[58:59], v[48:49] op_sel:[1,0,0] op_sel_hi:[1,1,1]
	v_pk_fma_f32 v[68:69], v[36:37], v[60:61], v[68:69] op_sel:[1,0,0] op_sel_hi:[1,1,1]
	v_fmac_f32_e32 v39, v38, v62
	ds_read2_b32 v[56:57], v35 offset0:103 offset1:104
	ds_read2_b32 v[58:59], v35 offset0:105 offset1:106
	ds_read2_b32 v[60:61], v35 offset0:107 offset1:108
	ds_read2_b32 v[62:63], v35 offset0:109 offset1:110
	s_waitcnt lgkmcnt(6)
	v_pk_fma_f32 v[40:41], v[38:39], v[64:65], v[40:41] op_sel:[0,0,0] op_sel_hi:[0,1,1]
	v_pk_fma_f32 v[42:43], v[38:39], v[72:73], v[42:43] op_sel:[0,0,0] op_sel_hi:[0,1,1]
	v_pk_fma_f32 v[44:45], v[38:39], v[74:75], v[44:45] op_sel:[0,0,0] op_sel_hi:[0,1,1]
	v_pk_fma_f32 v[46:47], v[38:39], v[76:77], v[46:47] op_sel:[0,0,0] op_sel_hi:[0,1,1]
	ds_read2_b32 v[64:65], v35 offset0:111 offset1:112
	ds_read2_b32 v[72:73], v35 offset0:113 offset1:114
	ds_read_b32 v74, v35 offset:548
	ds_read2_b32 v[76:77], v35 offset0:138 offset1:139
	s_waitcnt lgkmcnt(6)
	v_pk_fma_f32 v[48:49], v[38:39], v[52:53], v[48:49] op_sel:[0,0,0] op_sel_hi:[0,1,1]
	v_pk_fma_f32 v[68:69], v[38:39], v[54:55], v[68:69] op_sel:[0,0,0] op_sel_hi:[0,1,1]
	v_pk_fma_f32 v[40:41], v[38:39], v[56:57], v[40:41] op_sel:[1,0,0] op_sel_hi:[1,1,1]
	v_pk_fma_f32 v[42:43], v[38:39], v[58:59], v[42:43] op_sel:[1,0,0] op_sel_hi:[1,1,1]
	ds_read2_b32 v[52:53], v35 offset0:140 offset1:141
	ds_read2_b32 v[54:55], v35 offset0:142 offset1:143
	ds_read2_b32 v[56:57], v35 offset0:144 offset1:145
	ds_read2_b32 v[58:59], v35 offset0:146 offset1:147
	s_waitcnt lgkmcnt(6)
	v_pk_fma_f32 v[44:45], v[38:39], v[60:61], v[44:45] op_sel:[1,0,0] op_sel_hi:[1,1,1]
	v_pk_fma_f32 v[46:47], v[38:39], v[62:63], v[46:47] op_sel:[1,0,0] op_sel_hi:[1,1,1]
	v_pk_fma_f32 v[48:49], v[38:39], v[64:65], v[48:49] op_sel:[1,0,0] op_sel_hi:[1,1,1]
	v_pk_fma_f32 v[68:69], v[38:39], v[72:73], v[68:69] op_sel:[1,0,0] op_sel_hi:[1,1,1]
	ds_read2_b32 v[60:61], v35 offset0:171 offset1:172
	ds_read2_b32 v[62:63], v35 offset0:173 offset1:174
	ds_read2_b32 v[64:65], v35 offset0:175 offset1:176
	ds_read2_b32 v[72:73], v35 offset0:177 offset1:178
	s_waitcnt lgkmcnt(6)
	v_fmac_f32_e32 v41, v40, v74
	v_pk_fma_f32 v[42:43], v[40:41], v[76:77], v[42:43] op_sel:[0,0,0] op_sel_hi:[0,1,1]
	v_pk_fma_f32 v[44:45], v[40:41], v[52:53], v[44:45] op_sel:[0,0,0] op_sel_hi:[0,1,1]
	v_pk_fma_f32 v[46:47], v[40:41], v[54:55], v[46:47] op_sel:[0,0,0] op_sel_hi:[0,1,1]
	ds_read2_b32 v[74:75], v35 offset0:179 offset1:180
	ds_read_b32 v76, v35 offset:820
	ds_read2_b32 v[52:53], v35 offset0:206 offset1:207
	ds_read2_b32 v[54:55], v35 offset0:208 offset1:209
	s_waitcnt lgkmcnt(6)
	v_pk_fma_f32 v[48:49], v[40:41], v[56:57], v[48:49] op_sel:[0,0,0] op_sel_hi:[0,1,1]
	v_pk_fma_f32 v[68:69], v[40:41], v[58:59], v[68:69] op_sel:[0,0,0] op_sel_hi:[0,1,1]
	v_pk_fma_f32 v[42:43], v[40:41], v[60:61], v[42:43] op_sel:[1,0,0] op_sel_hi:[1,1,1]
	v_pk_fma_f32 v[44:45], v[40:41], v[62:63], v[44:45] op_sel:[1,0,0] op_sel_hi:[1,1,1]
	ds_read2_b32 v[56:57], v35 offset0:210 offset1:211
	ds_read2_b32 v[58:59], v35 offset0:212 offset1:213
	ds_read2_b32 v[60:61], v35 offset0:239 offset1:240
	ds_read2_b32 v[62:63], v35 offset0:241 offset1:242
	s_waitcnt lgkmcnt(6)
	v_pk_fma_f32 v[46:47], v[40:41], v[64:65], v[46:47] op_sel:[1,0,0] op_sel_hi:[1,1,1]
	v_pk_fma_f32 v[48:49], v[40:41], v[72:73], v[48:49] op_sel:[1,0,0] op_sel_hi:[1,1,1]
	v_pk_fma_f32 v[68:69], v[40:41], v[74:75], v[68:69] op_sel:[1,0,0] op_sel_hi:[1,1,1]
	v_fmac_f32_e32 v43, v42, v76
	ds_read2_b32 v[64:65], v35 offset0:243 offset1:244
	ds_read2_b32 v[72:73], v35 offset0:245 offset1:246
	ds_read_b32 v74, v50 offset:36
	ds_read2_b32 v[76:77], v50 offset0:10 offset1:11
	s_waitcnt lgkmcnt(6)
	v_pk_fma_f32 v[44:45], v[42:43], v[52:53], v[44:45] op_sel:[0,0,0] op_sel_hi:[0,1,1]
	v_pk_fma_f32 v[46:47], v[42:43], v[54:55], v[46:47] op_sel:[0,0,0] op_sel_hi:[0,1,1]
	v_pk_fma_f32 v[48:49], v[42:43], v[56:57], v[48:49] op_sel:[0,0,0] op_sel_hi:[0,1,1]
	v_pk_fma_f32 v[68:69], v[42:43], v[58:59], v[68:69] op_sel:[0,0,0] op_sel_hi:[0,1,1]
	ds_read2_b32 v[52:53], v50 offset0:12 offset1:13
	ds_read2_b32 v[54:55], v50 offset0:14 offset1:15
	ds_read2_b32 v[56:57], v50 offset0:43 offset1:44
	ds_read2_b32 v[58:59], v50 offset0:45 offset1:46
	s_waitcnt lgkmcnt(6)
	v_pk_fma_f32 v[44:45], v[42:43], v[60:61], v[44:45] op_sel:[1,0,0] op_sel_hi:[1,1,1]
	v_pk_fma_f32 v[46:47], v[42:43], v[62:63], v[46:47] op_sel:[1,0,0] op_sel_hi:[1,1,1]
	v_pk_fma_f32 v[48:49], v[42:43], v[64:65], v[48:49] op_sel:[1,0,0] op_sel_hi:[1,1,1]
	v_pk_fma_f32 v[68:69], v[42:43], v[72:73], v[68:69] op_sel:[1,0,0] op_sel_hi:[1,1,1]
	ds_read2_b32 v[60:61], v50 offset0:47 offset1:48
	ds_read_b32 v62, v50 offset:308
	ds_read2_b32 v[64:65], v50 offset0:78 offset1:79
	ds_read2_b32 v[72:73], v50 offset0:80 offset1:81
	s_waitcnt lgkmcnt(6)
	v_fmac_f32_e32 v45, v44, v74
	v_pk_fma_f32 v[46:47], v[44:45], v[76:77], v[46:47] op_sel:[0,0,0] op_sel_hi:[0,1,1]
	v_pk_fma_f32 v[48:49], v[44:45], v[52:53], v[48:49] op_sel:[0,0,0] op_sel_hi:[0,1,1]
	v_pk_fma_f32 v[68:69], v[44:45], v[54:55], v[68:69] op_sel:[0,0,0] op_sel_hi:[0,1,1]
	ds_read2_b32 v[74:75], v50 offset0:111 offset1:112
	ds_read2_b32 v[76:77], v50 offset0:113 offset1:114
	ds_read_b32 v52, v50 offset:580
	ds_read2_b32 v[54:55], v50 offset0:146 offset1:147
	s_waitcnt lgkmcnt(6)
	v_pk_fma_f32 v[46:47], v[44:45], v[56:57], v[46:47] op_sel:[1,0,0] op_sel_hi:[1,1,1]
	v_pk_fma_f32 v[48:49], v[44:45], v[58:59], v[48:49] op_sel:[1,0,0] op_sel_hi:[1,1,1]
	v_pk_fma_f32 v[68:69], v[44:45], v[60:61], v[68:69] op_sel:[1,0,0] op_sel_hi:[1,1,1]
	v_fmac_f32_e32 v47, v46, v62
	ds_read2_b32 v[56:57], v50 offset0:179 offset1:180
	ds_read_b32 v58, v50 offset:852
	s_waitcnt lgkmcnt(4)
	v_pk_fma_f32 v[48:49], v[46:47], v[64:65], v[48:49] op_sel:[0,0,0] op_sel_hi:[0,1,1]
	v_pk_fma_f32 v[68:69], v[46:47], v[72:73], v[68:69] op_sel:[0,0,0] op_sel_hi:[0,1,1]
	v_pk_fma_f32 v[48:49], v[46:47], v[74:75], v[48:49] op_sel:[1,0,0] op_sel_hi:[1,1,1]
	v_pk_fma_f32 v[68:69], v[46:47], v[76:77], v[68:69] op_sel:[1,0,0] op_sel_hi:[1,1,1]
	s_waitcnt lgkmcnt(0)
	v_fmac_f32_e32 v49, v48, v52
	v_pk_fma_f32 v[68:69], v[48:49], v[54:55], v[68:69] op_sel:[0,0,0] op_sel_hi:[0,1,1]
	v_pk_fma_f32 v[68:69], v[48:49], v[56:57], v[68:69] op_sel:[1,0,0] op_sel_hi:[1,1,1]
	v_fmac_f32_e32 v69, v68, v58
	v_mul_u32_u24_e32 v35, 0x440, v67
	v_mul_u32_u24_e32 v50, 0x520, v67
	v_mul_u32_u24_e32 v67, 0x44, v34
	v_add_u32_e32 v35, v35, v67
	v_lshl_add_u32 v50, v34, 1, v50
	v_add_u32_e32 v35, 0x3100, v35
	v_add_u32_e32 v50, 0xe3c0, v50
	ds_write2_b32 v35, v36, v37 offset0:0 offset1:1
	ds_write2_b32 v35, v38, v39 offset0:2 offset1:3
	ds_write2_b32 v35, v40, v41 offset0:4 offset1:5
	ds_write2_b32 v35, v42, v43 offset0:6 offset1:7
	ds_write2_b32 v35, v44, v45 offset0:8 offset1:9
	ds_write2_b32 v35, v46, v47 offset0:10 offset1:11
	ds_write2_b32 v35, v48, v49 offset0:12 offset1:13
	ds_write2_b32 v35, v68, v69 offset0:14 offset1:15
	v_cvt_pk_bf16_f32 v52, v36, v37
	ds_write_b16 v50, v52 offset:0
	ds_write_b16_d16_hi v50, v52 offset:80
	v_cvt_pk_bf16_f32 v54, v38, v39
	ds_write_b16 v50, v54 offset:160
	ds_write_b16_d16_hi v50, v54 offset:240
	v_cvt_pk_bf16_f32 v56, v40, v41
	ds_write_b16 v50, v56 offset:320
	ds_write_b16_d16_hi v50, v56 offset:400
	v_cvt_pk_bf16_f32 v58, v42, v43
	ds_write_b16 v50, v58 offset:480
	ds_write_b16_d16_hi v50, v58 offset:560
	v_cvt_pk_bf16_f32 v60, v44, v45
	ds_write_b16 v50, v60 offset:640
	ds_write_b16_d16_hi v50, v60 offset:720
	v_cvt_pk_bf16_f32 v62, v46, v47
	ds_write_b16 v50, v62 offset:800
	ds_write_b16_d16_hi v50, v62 offset:880
	v_cvt_pk_bf16_f32 v64, v48, v49
	ds_write_b16 v50, v64 offset:960
	ds_write_b16_d16_hi v50, v64 offset:1040
	v_cvt_pk_bf16_f32 v72, v68, v69
	ds_write_b16 v50, v72 offset:1120
	ds_write_b16_d16_hi v50, v72 offset:1200

.Lpf_skip_c:
	v_add3_u32 v50, s85, v66, v0
	ds_read_b128 v[34:37], v50
	v_add3_u32 v0, s86, v66, v0
	ds_read_b128 v[38:41], v0
	ds_read_b128 v[52:55], v50 offset:32
	ds_read_b128 v[56:59], v0 offset:32
	s_mov_b64 s[58:59], -1
	s_and_b64 vcc, exec, s[54:55]
	s_waitcnt lgkmcnt(2)
	v_mfma_f32_32x32x16_bf16 v[34:49], v[34:37], v[38:41], 0
	s_waitcnt lgkmcnt(0)
	v_mfma_f32_32x32x16_bf16 v[34:49], v[52:55], v[56:59], v[34:49]
	ds_read_b128 v[52:55], v50 offset:64
	ds_read_b128 v[56:59], v0 offset:64
	ds_read_b128 v[60:63], v50 offset:96
	ds_read_b128 v[72:75], v0 offset:96
	v_lshlrev_b32_e32 v0, 2, v51
	v_cmp_lt_u32_e64 s[12:13], v70, v0
	v_lshl_add_u32 v50, v70, 1, s87
	s_waitcnt lgkmcnt(2)
	v_mfma_f32_32x32x16_bf16 v[34:49], v[52:55], v[56:59], v[34:49]
	v_cndmask_b32_e64 v52, 0, 1, s[12:13]
	v_cmp_le_u32_e64 s[12:13], v70, v0
	s_nop 1
	v_cndmask_b32_e64 v53, 0, 1, s[12:13]
	v_cndmask_b32_e64 v52, v53, v52, s[8:9]
	v_and_b32_e32 v52, 1, v52
	s_waitcnt lgkmcnt(0)
	v_mfma_f32_32x32x16_bf16 v[34:49], v[60:63], v[72:75], v[34:49]
	v_sub_u32_e32 v143, v70, v0
	s_cmp_eq_u64 s[54:55], 0
	s_cbranch_scc1 .Ld_w0_c
	s_cmp_lg_u32 s85, s69
	s_cbranch_scc1 .Ld_w23_c
	v_mul_u32_u24_e32 v52, 0x50, v0
	v_add_u32_e32 v52, v52, v50
	v_cmp_gt_i32_e32 vcc, 0, v143
	v_cmp_gt_i32_e64 s[12:13], 1, v143
	v_cmp_gt_i32_e64 s[58:59], 2, v143
	v_cndmask_b32_e64 v34, 0, v34, vcc
	v_cmp_gt_i32_e32 vcc, 3, v143
	v_cndmask_b32_e64 v35, 0, v35, s[12:13]
	v_cmp_gt_i32_e64 s[12:13], 8, v143
	v_cvt_pk_bf16_f32 v53, v34, v35
	ds_write_b16 v52, v53 offset:0
	ds_write_b16_d16_hi v52, v53 offset:80
	v_cndmask_b32_e64 v36, 0, v36, s[58:59]
	v_cmp_gt_i32_e64 s[58:59], 9, v143
	v_cndmask_b32_e64 v37, 0, v37, vcc
	v_cmp_gt_i32_e32 vcc, 10, v143
	v_cvt_pk_bf16_f32 v53, v36, v37
	ds_write_b16 v52, v53 offset:160
	ds_write_b16_d16_hi v52, v53 offset:240
	v_cndmask_b32_e64 v38, 0, v38, s[12:13]
	v_cmp_gt_i32_e64 s[12:13], 11, v143
	v_cndmask_b32_e64 v39, 0, v39, s[58:59]
	v_cmp_gt_i32_e64 s[58:59], 16, v143
	v_cvt_pk_bf16_f32 v53, v38, v39
	ds_write_b16 v52, v53 offset:640
	ds_write_b16_d16_hi v52, v53 offset:720
	v_cndmask_b32_e64 v40, 0, v40, vcc
	v_cmp_gt_i32_e32 vcc, 17, v143
	v_cndmask_b32_e64 v41, 0, v41, s[12:13]
	v_cmp_gt_i32_e64 s[12:13], 18, v143
	v_cvt_pk_bf16_f32 v53, v40, v41
	ds_write_b16 v52, v53 offset:800
	ds_write_b16_d16_hi v52, v53 offset:880
	v_cndmask_b32_e64 v42, 0, v42, s[58:59]
	v_cmp_gt_i32_e64 s[58:59], 19, v143
	v_cndmask_b32_e64 v43, 0, v43, vcc
	v_cmp_gt_i32_e32 vcc, 24, v143
	v_cvt_pk_bf16_f32 v53, v42, v43
	ds_write_b16 v52, v53 offset:1280
	ds_write_b16_d16_hi v52, v53 offset:1360
	v_cndmask_b32_e64 v44, 0, v44, s[12:13]
	v_cmp_gt_i32_e64 s[12:13], 25, v143
	v_cndmask_b32_e64 v45, 0, v45, s[58:59]
	v_cmp_gt_i32_e64 s[58:59], 26, v143
	v_cvt_pk_bf16_f32 v53, v44, v45
	ds_write_b16 v52, v53 offset:1440
	ds_write_b16_d16_hi v52, v53 offset:1520
	v_cndmask_b32_e64 v46, 0, v46, vcc
	v_cmp_gt_i32_e32 vcc, 27, v143
	v_cndmask_b32_e64 v47, 0, v47, s[12:13]
	v_cvt_pk_bf16_f32 v53, v46, v47
	ds_write_b16 v52, v53 offset:1920
	ds_write_b16_d16_hi v52, v53 offset:2000
	v_cndmask_b32_e64 v48, 0, v48, s[58:59]
	v_cndmask_b32_e64 v49, 0, v49, vcc
	v_cvt_pk_bf16_f32 v53, v48, v49
	ds_write_b16 v52, v53 offset:2080
	ds_write_b16_d16_hi v52, v53 offset:2160
	s_branch .Ld_done_c
